# kept version with the P2 queue split moved from 3/8 to 4/8 of workgroups starting on the sample-attention queue (scheduling retune)
# speedup vs baseline: 1.0134x; 1.0134x over previous
; #define LBAR() do { asm volatile("s_waitcnt lgkmcnt(0)" ::: "memory"); __builtin_amdgcn_s_barrier(); asm volatile("" ::: "memory"); } while (0)
; __device__ __forceinline__ int p2_fetch(Frame& F, int cw) {
;     if (F.tid == 0) F.MISC[4] = __hip_atomic_fetch_add(F.ctl + cw, 1u, RLX_AGENT);
;     LBAR(); const int t = __builtin_amdgcn_readfirstlane((int)F.MISC[4]); LBAR(); return t;
; __device__ __forceinline__ void p2_run_b(Frame& F) {
;     if (!(F.item_mask & 8)) return;
;     const int t = p2_fetch(F, CW_TICKET);
;     if (t < N_ATTP) (void)attn_prompt_loop(F, t);
; }
; __device__ __forceinline__ void p2_phase(Frame& F) {
;     ...
;     if (F.item_mask & 64) {
;         if ((int)blockIdx.x < 16) { for (int i = (int)blockIdx.x; i < N_ATTS; i += 16) attn_sample_item(F, i >> 3, i & 7); }
;         return;
;     }
;     ...
;     if (F.item_mask & 1) { const int tg = p2_fetch(F, CW_TICKET_G); if (tg < N_GLAP) gla_prompt_item(F, tg >> 2, tg & 3); }
;     if ((((int)blockIdx.x >> 3) & 7) < 3) { p2_run_a(F); p2_run_b(F); } else { p2_run_b(F); p2_run_a(F); }
.LBB0_604:
	s_and_b32 s0, s2, 56
	s_cmp_gt_u32 s0, 31
	s_mov_b64 s[4:5], -1
	s_cbranch_scc0 .LBB0_854
	s_bitcmp0_b32 s62, 3
	s_cbranch_scc1 .LBB0_774
	v_cmp_eq_u32_e32 vcc, 0, v0
	s_and_saveexec_b64 s[4:5], vcc
	s_cbranch_execz .LBB0_610
	s_mov_b64 s[8:9], exec
	v_mbcnt_lo_u32_b32 v1, s8, 0
	v_mbcnt_hi_u32_b32 v1, s9, v1
	v_cmp_eq_u32_e32 vcc, 0, v1
	s_and_saveexec_b64 s[6:7], vcc
	s_cbranch_execz .LBB0_609
	s_bcnt1_i32_b64 s0, s[8:9]
	s_waitcnt vmcnt(0) lgkmcnt(0)
	v_mov_b32_e32 v2, 0
	v_mov_b32_e32 v3, s0
	global_atomic_add v2, v2, v3, s[58:59] offset:256 sc0
